# P4/P8 out-proj GEMM: half the blocks start ~13us late so epilogues overlap other blocks' main loops
# baseline (speedup 1.0000x reference)
.LBB0_420:
	s_bitcmp1_b32 s92, 3
	s_cbranch_scc0 .Ldephase4
	s_sleep 127
	s_sleep 127
	s_sleep 127
	s_sleep 127
